# P4 pass epilogue: z (silu gate) loads requested at the start of the epilogue into registers released by the tile loop
# speedup vs baseline: 1.0208x; 1.0051x over previous
.LBB0_682:
	s_cmp_lg_u32 s67, s62
	s_cbranch_scc1 .Lzh_skip
	s_add_i32 s76, s65, s63
	s_ashr_i32 s77, s76, 31
	s_add_i32 s78, s66, s63
	s_lshl_b64 s[76:77], s[76:77], 23
	v_lshl_add_u64 v[234:235], v[170:171], 0, s[76:77]
	s_ashr_i32 s79, s78, 31
	s_lshl_b64 s[78:79], s[78:79], 23
	v_lshl_add_u64 v[236:237], v[170:171], 0, s[78:79]
	global_load_dwordx4 v[214:217], v[234:235], off
	global_load_dwordx4 v[218:221], v[236:237], off
	global_load_dwordx4 v[222:225], v[234:235], off offset:32
	global_load_dwordx4 v[226:229], v[236:237], off offset:32
	global_load_dwordx4 v[230:233], v[234:235], off offset:64
	global_load_dwordx4 v[244:247], v[234:235], off offset:96
	global_load_dwordx4 v[248:251], v[236:237], off offset:64
	global_load_dwordx4 v[252:255], v[236:237], off offset:96

.LBB0_686:
	s_nop 0
	v_div_scale_f32 v3, s[0:1], v4, v4, 1.0
	v_rcp_f32_e32 v6, v3
	v_div_scale_f32 v7, vcc, 1.0, v4, 1.0
	v_fma_f32 v8, -v3, v6, 1.0
	v_fmac_f32_e32 v6, v8, v6
	v_mul_f32_e32 v8, v7, v6
	v_fma_f32 v9, -v3, v8, v7
	v_fmac_f32_e32 v8, v9, v6
	v_fma_f32 v3, -v3, v8, v7
	v_div_fmas_f32 v3, v3, v6, v8
	v_div_scale_f32 v6, s[0:1], v5, v5, 1.0
	v_rcp_f32_e32 v7, v6
	v_div_fixup_f32 v3, v3, v4, 1.0
	v_cmp_lt_f32_e32 vcc, 0, v4
	s_nop 1
	v_cndmask_b32_e32 v3, 0, v3, vcc
	s_cmp_eq_u32 s11, 2
	s_cbranch_scc1 .Lgw8
	s_cmp_eq_u32 s67, s62
	s_cbranch_scc1 .Lgwz
	s_waitcnt vmcnt(0)
	s_branch .Lgw1
.Lgwz:
	s_waitcnt vmcnt(8)
	s_branch .Lgw1
.Lgw8:
	s_waitcnt vmcnt(16)

.LBB0_691:
	s_add_i32 s65, s65, s53
	s_add_i32 s66, s66, s53
	s_lshl_b32 s0, s65, 6
	s_lshl_b32 s1, s66, 6
	s_add_i32 s24, s0, s47
	s_add_i32 s0, s1, s47
	s_ashr_i32 s25, s24, 31
	s_ashr_i32 s1, s0, 31
	v_lshl_add_u64 v[82:83], s[24:25], 1, v[176:177]
	v_lshl_add_u64 v[66:67], s[0:1], 1, v[176:177]
	s_waitcnt vmcnt(0)
	v_mov_b64_e32 v[28:29], v[214:215]
	v_mov_b64_e32 v[30:31], v[216:217]
	v_mov_b64_e32 v[24:25], v[218:219]
	v_mov_b64_e32 v[26:27], v[220:221]
	v_mov_b64_e32 v[4:5], v[222:223]
	v_mov_b64_e32 v[6:7], v[224:225]
	v_mov_b64_e32 v[36:37], v[226:227]
	v_mov_b64_e32 v[38:39], v[228:229]
	v_mov_b64_e32 v[32:33], v[230:231]
	v_mov_b64_e32 v[34:35], v[232:233]
	v_mov_b64_e32 v[12:13], v[244:245]
	v_mov_b64_e32 v[14:15], v[246:247]
	v_mov_b64_e32 v[20:21], v[248:249]
	v_mov_b64_e32 v[22:23], v[250:251]
	v_mov_b64_e32 v[8:9], v[252:253]
	v_mov_b64_e32 v[10:11], v[254:255]
	v_mov_b32_e32 v3, v30
	v_mov_b32_e32 v109, v26
	v_mov_b32_e32 v111, v27
	v_permlane32_swap_b32_e32 v28, v3
	v_permlane32_swap_b32_e32 v29, v31
	v_mov_b32_e32 v114, v6
	v_mov_b32_e32 v115, v7
	v_permlane32_swap_b32_e32 v24, v109
	v_permlane32_swap_b32_e32 v25, v111
	v_lshlrev_b32_e32 v6, 16, v28
	v_and_b32_e32 v7, 0xffff0000, v28
	v_lshlrev_b32_e32 v26, 16, v29
	v_and_b32_e32 v27, 0xffff0000, v29
	v_lshlrev_b32_e32 v28, 16, v3
	v_and_b32_e32 v29, 0xffff0000, v3
	v_lshlrev_b32_e32 v30, 16, v31
	v_and_b32_e32 v31, 0xffff0000, v31
	v_permlane32_swap_b32_e32 v5, v115
	v_lshlrev_b32_e32 v106, 16, v24
	v_and_b32_e32 v107, 0xffff0000, v24
	v_lshlrev_b32_e32 v24, 16, v25
	v_and_b32_e32 v25, 0xffff0000, v25
	v_lshlrev_b32_e32 v108, 16, v109
	v_and_b32_e32 v109, 0xffff0000, v109
	v_lshlrev_b32_e32 v110, 16, v111
	v_and_b32_e32 v111, 0xffff0000, v111
	v_pk_mul_f32 v[6:7], v[88:89], v[6:7]
	v_pk_mul_f32 v[26:27], v[92:93], v[26:27]
	v_pk_mul_f32 v[28:29], v[98:99], v[28:29]
	v_pk_mul_f32 v[30:31], v[102:103], v[30:31]
	v_pk_mul_f32 v[88:89], v[90:91], v[106:107]
	v_pk_mul_f32 v[90:91], v[96:97], v[24:25]
	v_pk_mul_f32 v[92:93], v[100:101], v[108:109]
	v_pk_mul_f32 v[96:97], v[104:105], v[110:111]
	v_cvt_pk_bf16_f32 v24, v6, v7
	v_cvt_pk_bf16_f32 v25, v26, v27
	v_cvt_pk_bf16_f32 v26, v28, v29
	v_cvt_pk_bf16_f32 v27, v30, v31
	v_lshlrev_b32_e32 v6, 16, v5
	v_and_b32_e32 v7, 0xffff0000, v5
	v_permlane32_swap_b32_e32 v4, v114
	v_cvt_pk_bf16_f32 v28, v88, v89
	v_cvt_pk_bf16_f32 v29, v90, v91
	v_cvt_pk_bf16_f32 v30, v92, v93
	v_cvt_pk_bf16_f32 v31, v96, v97
	v_permlane32_swap_b32_e32 v24, v26
	v_permlane32_swap_b32_e32 v25, v27
	v_pk_mul_f32 v[6:7], v[76:77], v[6:7]
	v_lshlrev_b32_e32 v112, 16, v4
	v_and_b32_e32 v113, 0xffff0000, v4
	v_permlane32_swap_b32_e32 v28, v30
	v_permlane32_swap_b32_e32 v29, v31
	global_store_dwordx4 v[82:83], v[24:27], off
	global_store_dwordx4 v[66:67], v[28:31], off
	v_cvt_pk_bf16_f32 v5, v6, v7
	v_lshlrev_b32_e32 v6, 16, v114
	v_and_b32_e32 v7, 0xffff0000, v114
	v_lshlrev_b32_e32 v24, 16, v115
	v_and_b32_e32 v25, 0xffff0000, v115
	v_pk_mul_f32 v[94:95], v[94:95], v[112:113]
	v_pk_mul_f32 v[6:7], v[78:79], v[6:7]
	v_pk_mul_f32 v[24:25], v[80:81], v[24:25]
	v_cvt_pk_bf16_f32 v4, v94, v95
	v_cvt_pk_bf16_f32 v6, v6, v7
	v_cvt_pk_bf16_f32 v7, v24, v25
	v_mov_b32_e32 v3, v38
	v_mov_b32_e32 v25, v39
	v_permlane32_swap_b32_e32 v4, v6
	v_permlane32_swap_b32_e32 v5, v7
	v_permlane32_swap_b32_e32 v36, v3
	v_permlane32_swap_b32_e32 v37, v25
	global_store_dwordx4 v[82:83], v[4:7], off offset:32
	v_lshlrev_b32_e32 v24, 16, v25
	v_and_b32_e32 v25, 0xffff0000, v25
	v_lshlrev_b32_e32 v4, 16, v36
	v_and_b32_e32 v5, 0xffff0000, v36
	v_lshlrev_b32_e32 v6, 16, v37
	v_and_b32_e32 v7, 0xffff0000, v37
	v_pk_mul_f32 v[4:5], v[74:75], v[4:5]
	v_pk_mul_f32 v[6:7], v[60:61], v[6:7]
	v_cvt_pk_bf16_f32 v4, v4, v5
	v_cvt_pk_bf16_f32 v5, v6, v7
	v_lshlrev_b32_e32 v6, 16, v3
	v_and_b32_e32 v7, 0xffff0000, v3
	v_pk_mul_f32 v[6:7], v[62:63], v[6:7]
	v_pk_mul_f32 v[24:25], v[64:65], v[24:25]
	v_cvt_pk_bf16_f32 v6, v6, v7
	v_cvt_pk_bf16_f32 v7, v24, v25
	v_mov_b32_e32 v3, v34
	v_mov_b32_e32 v25, v35
	v_permlane32_swap_b32_e32 v4, v6
	v_permlane32_swap_b32_e32 v5, v7
	v_permlane32_swap_b32_e32 v32, v3
	v_permlane32_swap_b32_e32 v33, v25
	global_store_dwordx4 v[66:67], v[4:7], off offset:32
	v_lshlrev_b32_e32 v24, 16, v25
	v_and_b32_e32 v25, 0xffff0000, v25
	v_lshlrev_b32_e32 v4, 16, v32
	v_and_b32_e32 v5, 0xffff0000, v32
	v_lshlrev_b32_e32 v6, 16, v33
	v_and_b32_e32 v7, 0xffff0000, v33
	v_pk_mul_f32 v[4:5], v[84:85], v[4:5]
	v_pk_mul_f32 v[6:7], v[86:87], v[6:7]
	v_cvt_pk_bf16_f32 v4, v4, v5
	v_cvt_pk_bf16_f32 v5, v6, v7
	v_lshlrev_b32_e32 v6, 16, v3
	v_and_b32_e32 v7, 0xffff0000, v3
	v_pk_mul_f32 v[6:7], v[70:71], v[6:7]
	v_pk_mul_f32 v[24:25], v[72:73], v[24:25]
	v_cvt_pk_bf16_f32 v6, v6, v7
	v_cvt_pk_bf16_f32 v7, v24, v25
	v_mov_b32_e32 v3, v22
	v_mov_b32_e32 v22, v23
	v_permlane32_swap_b32_e32 v4, v6
	v_permlane32_swap_b32_e32 v5, v7
	v_permlane32_swap_b32_e32 v20, v3
	v_permlane32_swap_b32_e32 v21, v22
	global_store_dwordx4 v[82:83], v[4:7], off offset:64
	s_nop 1
	v_lshlrev_b32_e32 v4, 16, v20
	v_and_b32_e32 v5, 0xffff0000, v20
	v_lshlrev_b32_e32 v6, 16, v21
	v_and_b32_e32 v7, 0xffff0000, v21
	v_pk_mul_f32 v[4:5], v[68:69], v[4:5]
	v_pk_mul_f32 v[6:7], v[54:55], v[6:7]
	v_cvt_pk_bf16_f32 v4, v4, v5
	v_cvt_pk_bf16_f32 v5, v6, v7
	v_lshlrev_b32_e32 v6, 16, v3
	v_and_b32_e32 v7, 0xffff0000, v3
	v_lshlrev_b32_e32 v20, 16, v22
	v_and_b32_e32 v21, 0xffff0000, v22
	v_pk_mul_f32 v[6:7], v[56:57], v[6:7]
	v_pk_mul_f32 v[20:21], v[58:59], v[20:21]
	v_cvt_pk_bf16_f32 v6, v6, v7
	v_cvt_pk_bf16_f32 v7, v20, v21
	v_mov_b32_e32 v3, v14
	v_mov_b32_e32 v14, v15
	v_permlane32_swap_b32_e32 v4, v6
	v_permlane32_swap_b32_e32 v5, v7
	v_permlane32_swap_b32_e32 v12, v3
	v_permlane32_swap_b32_e32 v13, v14
	global_store_dwordx4 v[66:67], v[4:7], off offset:64
	s_nop 1
	v_lshlrev_b32_e32 v4, 16, v12
	v_and_b32_e32 v5, 0xffff0000, v12
	v_lshlrev_b32_e32 v6, 16, v13
	v_and_b32_e32 v7, 0xffff0000, v13
	v_pk_mul_f32 v[4:5], v[52:53], v[4:5]
	v_pk_mul_f32 v[6:7], v[46:47], v[6:7]
	v_cvt_pk_bf16_f32 v4, v4, v5
	v_cvt_pk_bf16_f32 v5, v6, v7
	v_lshlrev_b32_e32 v6, 16, v3
	v_and_b32_e32 v7, 0xffff0000, v3
	v_lshlrev_b32_e32 v12, 16, v14
	v_and_b32_e32 v13, 0xffff0000, v14
	v_pk_mul_f32 v[6:7], v[48:49], v[6:7]
	v_pk_mul_f32 v[12:13], v[50:51], v[12:13]
	v_cvt_pk_bf16_f32 v6, v6, v7
	v_cvt_pk_bf16_f32 v7, v12, v13
	v_mov_b32_e32 v3, v10
	v_mov_b32_e32 v10, v11
	v_permlane32_swap_b32_e32 v4, v6
	v_permlane32_swap_b32_e32 v5, v7
	v_permlane32_swap_b32_e32 v8, v3
	v_permlane32_swap_b32_e32 v9, v10
	global_store_dwordx4 v[82:83], v[4:7], off offset:96
	s_nop 1
	v_lshlrev_b32_e32 v4, 16, v8
	v_and_b32_e32 v5, 0xffff0000, v8
	v_lshlrev_b32_e32 v6, 16, v9
	v_and_b32_e32 v7, 0xffff0000, v9
	v_pk_mul_f32 v[4:5], v[16:17], v[4:5]
	v_pk_mul_f32 v[6:7], v[40:41], v[6:7]
	v_cvt_pk_bf16_f32 v4, v4, v5
	v_cvt_pk_bf16_f32 v5, v6, v7
	v_lshlrev_b32_e32 v6, 16, v3
	v_and_b32_e32 v7, 0xffff0000, v3
	v_lshlrev_b32_e32 v8, 16, v10
	v_and_b32_e32 v9, 0xffff0000, v10
	v_pk_mul_f32 v[6:7], v[42:43], v[6:7]
	v_pk_mul_f32 v[8:9], v[44:45], v[8:9]
	v_cvt_pk_bf16_f32 v6, v6, v7
	v_cvt_pk_bf16_f32 v7, v8, v9
	s_nop 0
	v_permlane32_swap_b32_e32 v4, v6
	v_permlane32_swap_b32_e32 v5, v7
	global_store_dwordx4 v[66:67], v[4:7], off offset:96
	s_branch .LBB0_621
